# gate GEMM epilogue: hoist the 3rd/4th bias loads next to the first two (dead fragment VGPRs), removes two vmcnt(0) drains behind 64 bf16 stores per tile
# baseline (speedup 1.0000x reference)
; __device__ __forceinline__ uint32_t pk2(float lo, float hi) { typedef float f2 __attribute__((ext_vector_type(2))); const f2 v = {lo, hi}; return __builtin_bit_cast(uint32_t, __builtin_convertvector(v, bf16x2_t)); }
; __device__ __forceinline__ float sigmf(float x) { return __builtin_amdgcn_rcpf(1.f + __expf(-x)); }
; #define ZERO_ACC4(acc) { _Pragma("unroll") for (int _a = 0; _a < 2; ++_a) { _Pragma("unroll") for (int _b = 0; _b < 4; ++_b) { _Pragma("unroll") for (int _c = 0; _c < 16; ++_c) acc[_a][_b][_c] = 0.f; } } }
; __device__ __forceinline__ void phase_gate(const Params& p, int l, int b, unsigned char* lds) {
;     ...
;     for (int k = 0; tile_at(k, TH / 128, 12, pm, pn); ++k) {
;         f32x16 acc[2][4]; ZERO_ACC4(acc);
;         gemm_big(hb + (size_t)pm * 128 * DM, DM, wg + (size_t)pn * 256 * DM, DM, acc, lds);
; #pragma unroll
;         for (int ni = 0; ni < 4; ++ni) {
;             const int n = pn * 256 + wc * 128 + ni * 32 + r;
;             const float bias = bg[n];
; #pragma unroll
;             for (int mi = 0; mi < 2; ++mi)
; #pragma unroll
;                 for (int reg = 0; reg < 16; ++reg) {
;                     const int m = pm * 128 + wr * 64 + mi * 32 + (reg & 3) + 8 * (reg >> 2) + 4 * h;
;                     G[(size_t)m * 3072 + n] = (bf16_t)(pk2(sigmf(acc[mi][ni][reg] + bias), 0.f) & 0xffff);
;                 }
;         }
.LBB0_111:
	s_waitcnt vmcnt(9)
	v_lshl_or_b32 v138, s4, 8, v181
	v_ashrrev_i32_e32 v139, 31, v138
	v_lshl_add_u64 v[136:137], v[138:139], 2, s[24:25]
	global_load_dword v133, v[136:137], off
	global_load_dword v166, v[136:137], off offset:128
	global_load_dword v200, v[136:137], off offset:256
	global_load_dword v201, v[136:137], off offset:384
	v_lshl_add_u32 v132, s15, 7, v186
	v_lshl_add_u64 v[130:131], v[138:139], 1, s[20:21]
	v_mad_i64_i32 v[134:135], s[4:5], v132, s66, v[130:131]
	s_waitcnt vmcnt(8)
	v_or_b32_e32 v158, 16, v132
	v_or_b32_e32 v159, 17, v132
	v_or_b32_e32 v160, 18, v132
	v_or_b32_e32 v161, 19, v132
	s_waitcnt vmcnt(7)
	v_or_b32_e32 v162, 24, v132
	v_or_b32_e32 v163, 25, v132
	v_or_b32_e32 v164, 26, v132
	v_or_b32_e32 v165, 27, v132
	v_or_b32_e32 v0, 32, v132
	v_or_b32_e32 v139, 33, v132
	v_or_b32_e32 v144, 34, v132
	v_or_b32_e32 v145, 35, v132
	v_or_b32_e32 v146, 40, v132
	v_or_b32_e32 v147, 41, v132
	v_or_b32_e32 v148, 42, v132
	v_or_b32_e32 v149, 43, v132
	v_or_b32_e32 v150, 48, v132
	v_or_b32_e32 v151, 49, v132
	v_or_b32_e32 v152, 50, v132
	v_or_b32_e32 v153, 51, v132
	v_or_b32_e32 v154, 56, v132
	v_or_b32_e32 v155, 57, v132
	v_or_b32_e32 v156, 58, v132
	v_or_b32_e32 v157, 59, v132
	v_mov_b64_e32 v[140:141], s[20:21]
	s_add_i32 s14, s14, 1
	s_waitcnt vmcnt(3)
	v_add_f32_e32 v114, v114, v133
	v_mul_f32_e32 v114, 0xbfb8aa3b, v114
	v_exp_f32_e32 v114, v114
	v_add_f32_e32 v115, v115, v133
	v_mul_f32_e32 v115, 0xbfb8aa3b, v115
	v_exp_f32_e32 v115, v115
	v_add_f32_e32 v116, v116, v133
	v_mul_f32_e32 v116, 0xbfb8aa3b, v116
	v_add_f32_e32 v114, 1.0, v114
	v_exp_f32_e32 v116, v116
	v_add_f32_e32 v117, v117, v133
	v_rcp_f32_e32 v114, v114
	v_mul_f32_e32 v117, 0xbfb8aa3b, v117
	v_add_f32_e32 v115, 1.0, v115
	v_exp_f32_e32 v117, v117
	v_add_f32_e32 v118, v118, v133
	v_rcp_f32_e32 v115, v115
	v_mul_f32_e32 v118, 0xbfb8aa3b, v118
	v_add_f32_e32 v116, 1.0, v116
	v_exp_f32_e32 v118, v118
	v_add_f32_e32 v119, v119, v133
	v_cvt_pk_bf16_f32 v114, v114, s0
	v_rcp_f32_e32 v116, v116
	v_mul_f32_e32 v119, 0xbfb8aa3b, v119
	global_store_short v[134:135], v114, off
	v_or_b32_e32 v114, 1, v132
	v_add_f32_e32 v117, 1.0, v117
	v_exp_f32_e32 v119, v119
	v_add_f32_e32 v120, v120, v133
	v_cvt_pk_bf16_f32 v115, v115, s0
	v_mad_i64_i32 v[134:135], s[4:5], v114, s66, v[130:131]
	v_rcp_f32_e32 v117, v117
	v_mul_f32_e32 v120, 0xbfb8aa3b, v120
	global_store_short v[134:135], v115, off
	v_or_b32_e32 v115, 2, v132
	v_add_f32_e32 v118, 1.0, v118
	v_exp_f32_e32 v120, v120
	v_add_f32_e32 v121, v121, v133
	v_cvt_pk_bf16_f32 v116, v116, s0
	v_mad_i64_i32 v[134:135], s[4:5], v115, s66, v[130:131]
	v_rcp_f32_e32 v118, v118
	v_mul_f32_e32 v121, 0xbfb8aa3b, v121
	global_store_short v[134:135], v116, off
	v_or_b32_e32 v116, 3, v132
	v_add_f32_e32 v119, 1.0, v119
	v_exp_f32_e32 v121, v121
	v_cvt_pk_bf16_f32 v117, v117, s0
	v_mad_i64_i32 v[134:135], s[4:5], v116, s66, v[130:131]
	v_rcp_f32_e32 v119, v119
	global_store_short v[134:135], v117, off
	v_or_b32_e32 v117, 8, v132
	v_add_f32_e32 v120, 1.0, v120
	v_cvt_pk_bf16_f32 v118, v118, s0
	v_mad_i64_i32 v[134:135], s[4:5], v117, s66, v[130:131]
	v_rcp_f32_e32 v120, v120
	global_store_short v[134:135], v118, off
	v_or_b32_e32 v118, 9, v132
	v_add_f32_e32 v121, 1.0, v121
	v_cvt_pk_bf16_f32 v119, v119, s0
	v_mad_i64_i32 v[134:135], s[4:5], v118, s66, v[130:131]
	v_rcp_f32_e32 v121, v121
	global_store_short v[134:135], v119, off
	v_or_b32_e32 v119, 10, v132
	v_cvt_pk_bf16_f32 v120, v120, s0
	v_mad_i64_i32 v[134:135], s[4:5], v119, s66, v[130:131]
	global_store_short v[134:135], v120, off
	v_or_b32_e32 v120, 11, v132
	v_cvt_pk_bf16_f32 v121, v121, s0
	v_mad_i64_i32 v[134:135], s[4:5], v120, s66, v[130:131]
	global_store_short v[134:135], v121, off
	v_add_f32_e32 v121, v122, v133
	v_mul_f32_e32 v121, 0xbfb8aa3b, v121
	v_exp_f32_e32 v121, v121
	v_mad_i64_i32 v[134:135], s[4:5], v158, s66, v[130:131]
	v_add_f32_e32 v98, v98, v133
	v_add_f32_e32 v121, 1.0, v121
	v_rcp_f32_e32 v121, v121
	v_mul_f32_e32 v98, 0xbfb8aa3b, v98
	v_exp_f32_e32 v98, v98
	s_waitcnt vmcnt(10)
	v_add_f32_e32 v82, v82, v166
	v_cvt_pk_bf16_f32 v121, v121, s0
	global_store_short v[134:135], v121, off
	v_add_f32_e32 v121, v123, v133
	v_mul_f32_e32 v121, 0xbfb8aa3b, v121
	v_exp_f32_e32 v121, v121
	v_mad_i64_i32 v[122:123], s[4:5], v159, s66, v[130:131]
	v_add_f32_e32 v98, 1.0, v98
	v_add_f32_e32 v121, 1.0, v121
	v_rcp_f32_e32 v121, v121
	v_rcp_f32_e32 v98, v98
	v_mul_f32_e32 v82, 0xbfb8aa3b, v82
	v_exp_f32_e32 v82, v82
	v_cvt_pk_bf16_f32 v121, v121, s0
	global_store_short v[122:123], v121, off
	v_add_f32_e32 v121, v124, v133
	v_mul_f32_e32 v121, 0xbfb8aa3b, v121
	v_exp_f32_e32 v121, v121
	v_mad_i64_i32 v[122:123], s[4:5], v160, s66, v[130:131]
	v_cvt_pk_bf16_f32 v98, v98, s0
	v_add_f32_e32 v121, 1.0, v121
	v_rcp_f32_e32 v121, v121
	v_add_f32_e32 v82, 1.0, v82
	v_rcp_f32_e32 v82, v82
	v_mad_i64_i32 v[134:135], s[4:5], v132, s66, v[140:141]
	v_cvt_pk_bf16_f32 v121, v121, s0
	global_store_short v[122:123], v121, off
	v_add_f32_e32 v121, v125, v133
	v_mul_f32_e32 v121, 0xbfb8aa3b, v121
	v_exp_f32_e32 v121, v121
	v_mad_i64_i32 v[122:123], s[4:5], v161, s66, v[130:131]
	v_cvt_pk_bf16_f32 v82, v82, s0
	v_add_f32_e32 v121, 1.0, v121
	v_rcp_f32_e32 v121, v121
	v_mad_i64_i32 v[124:125], s[4:5], v118, s66, v[140:141]
	v_add_f32_e32 v66, v66, v166
	v_cvt_pk_bf16_f32 v121, v121, s0
	global_store_short v[122:123], v121, off
	v_add_f32_e32 v121, v126, v133
	v_mul_f32_e32 v121, 0xbfb8aa3b, v121
	v_exp_f32_e32 v121, v121
	v_mad_i64_i32 v[122:123], s[4:5], v162, s66, v[130:131]
	v_mul_f32_e32 v66, 0xbfb8aa3b, v66
	v_add_f32_e32 v121, 1.0, v121
	v_rcp_f32_e32 v121, v121
; __device__ __forceinline__ uint32_t pk2(float lo, float hi) { typedef float f2 __attribute__((ext_vector_type(2))); const f2 v = {lo, hi}; return __builtin_bit_cast(uint32_t, __builtin_convertvector(v, bf16x2_t)); }
; __device__ __forceinline__ float sigmf(float x) { return __builtin_amdgcn_rcpf(1.f + __expf(-x)); }
; __device__ __forceinline__ void phase_gate(const Params& p, int l, int b, unsigned char* lds) {
;     ...
; #pragma unroll
;         for (int ni = 0; ni < 4; ++ni) {
;             const int n = pn * 256 + wc * 128 + ni * 32 + r;
;             const float bias = bg[n];
; #pragma unroll
;             for (int mi = 0; mi < 2; ++mi)
; #pragma unroll
;                 for (int reg = 0; reg < 16; ++reg) {
;                     const int m = pm * 128 + wr * 64 + mi * 32 + (reg & 3) + 8 * (reg >> 2) + 4 * h;
;                     G[(size_t)m * 3072 + n] = (bf16_t)(pk2(sigmf(acc[mi][ni][reg] + bias), 0.f) & 0xffff);
;                 }
;         }
	v_exp_f32_e32 v66, v66
	v_cvt_pk_bf16_f32 v121, v121, s0
	global_store_short v[122:123], v121, off
	v_add_f32_e32 v121, v127, v133
	v_mul_f32_e32 v121, 0xbfb8aa3b, v121
	v_exp_f32_e32 v121, v121
	v_mad_i64_i32 v[122:123], s[4:5], v163, s66, v[130:131]
	v_mad_i64_i32 v[126:127], s[4:5], v117, s66, v[140:141]
	v_add_f32_e32 v121, 1.0, v121
	v_rcp_f32_e32 v121, v121
	v_add_f32_e32 v66, 1.0, v66
	v_rcp_f32_e32 v66, v66
	v_cvt_pk_bf16_f32 v121, v121, s0
	global_store_short v[122:123], v121, off
	v_add_f32_e32 v121, v128, v133
	v_mul_f32_e32 v121, 0xbfb8aa3b, v121
	v_exp_f32_e32 v121, v121
	v_mad_i64_i32 v[122:123], s[4:5], v164, s66, v[130:131]
	v_cvt_pk_bf16_f32 v66, v66, s0
	v_add_f32_e32 v121, 1.0, v121
	v_rcp_f32_e32 v121, v121
	s_nop 0
	v_cvt_pk_bf16_f32 v121, v121, s0
	global_store_short v[122:123], v121, off
	v_add_f32_e32 v121, v129, v133
	v_mul_f32_e32 v121, 0xbfb8aa3b, v121
	v_exp_f32_e32 v121, v121
	v_mad_i64_i32 v[122:123], s[4:5], v165, s66, v[130:131]
	v_mad_i64_i32 v[128:129], s[4:5], v116, s66, v[140:141]
	v_add_f32_e32 v121, 1.0, v121
	v_rcp_f32_e32 v121, v121
	v_mad_i64_i32 v[116:117], s[4:5], v159, s66, v[140:141]
	v_cvt_pk_bf16_f32 v121, v121, s0
	global_store_short v[122:123], v121, off
	v_mad_i64_i32 v[122:123], s[4:5], v0, s66, v[130:131]
	global_store_short v[122:123], v98, off
	v_add_f32_e32 v98, v99, v133
	v_mul_f32_e32 v98, 0xbfb8aa3b, v98
	v_exp_f32_e32 v98, v98
	v_mad_i64_i32 v[122:123], s[4:5], v119, s66, v[140:141]
	v_mad_i64_i32 v[118:119], s[4:5], v158, s66, v[140:141]
	v_add_f32_e32 v98, 1.0, v98
	v_rcp_f32_e32 v98, v98
	s_nop 0
	v_cvt_pk_bf16_f32 v121, v98, s0
	v_mad_i64_i32 v[98:99], s[4:5], v139, s66, v[130:131]
	global_store_short v[98:99], v121, off
	v_add_f32_e32 v98, v100, v133
	v_mul_f32_e32 v98, 0xbfb8aa3b, v98
	v_exp_f32_e32 v98, v98
	v_mad_i64_i32 v[120:121], s[4:5], v120, s66, v[140:141]
	v_add_f32_e32 v98, 1.0, v98
	v_rcp_f32_e32 v98, v98
	s_nop 0
	v_cvt_pk_bf16_f32 v100, v98, s0
	v_mad_i64_i32 v[98:99], s[4:5], v144, s66, v[130:131]
	global_store_short v[98:99], v100, off
	v_add_f32_e32 v98, v101, v133
	v_mul_f32_e32 v98, 0xbfb8aa3b, v98
	v_exp_f32_e32 v98, v98
	s_nop 0
	v_add_f32_e32 v98, 1.0, v98
	v_rcp_f32_e32 v98, v98
	s_nop 0
	v_cvt_pk_bf16_f32 v100, v98, s0
	v_mad_i64_i32 v[98:99], s[4:5], v145, s66, v[130:131]
	global_store_short v[98:99], v100, off
	v_add_f32_e32 v98, v102, v133
	v_mul_f32_e32 v98, 0xbfb8aa3b, v98
	v_exp_f32_e32 v98, v98
	s_nop 0
	v_add_f32_e32 v98, 1.0, v98
	v_rcp_f32_e32 v98, v98
	s_nop 0
	v_cvt_pk_bf16_f32 v100, v98, s0
	v_mad_i64_i32 v[98:99], s[4:5], v146, s66, v[130:131]
	global_store_short v[98:99], v100, off
	v_add_f32_e32 v98, v103, v133
	v_mul_f32_e32 v98, 0xbfb8aa3b, v98
	v_exp_f32_e32 v98, v98
	v_mad_i64_i32 v[102:103], s[4:5], v0, s66, v[140:141]
	v_add_f32_e32 v0, v67, v166
	v_add_f32_e32 v98, 1.0, v98
	v_rcp_f32_e32 v98, v98
	v_mul_f32_e32 v0, 0xbfb8aa3b, v0
	v_exp_f32_e32 v0, v0
	v_cvt_pk_bf16_f32 v100, v98, s0
	v_mad_i64_i32 v[98:99], s[4:5], v147, s66, v[130:131]
	global_store_short v[98:99], v100, off
	v_add_f32_e32 v98, v104, v133
	v_mul_f32_e32 v98, 0xbfb8aa3b, v98
	v_exp_f32_e32 v98, v98
	v_add_f32_e32 v0, 1.0, v0
	v_rcp_f32_e32 v0, v0
	v_add_f32_e32 v98, 1.0, v98
	v_rcp_f32_e32 v98, v98
	v_cvt_pk_bf16_f32 v0, v0, s0
	v_cvt_pk_bf16_f32 v100, v98, s0
	v_mad_i64_i32 v[98:99], s[4:5], v148, s66, v[130:131]
	global_store_short v[98:99], v100, off
	v_add_f32_e32 v98, v105, v133
	v_mul_f32_e32 v98, 0xbfb8aa3b, v98
	v_exp_f32_e32 v98, v98
	v_mad_i64_i32 v[104:105], s[4:5], v165, s66, v[140:141]
	v_add_f32_e32 v98, 1.0, v98
	v_rcp_f32_e32 v98, v98
	s_nop 0
	v_cvt_pk_bf16_f32 v100, v98, s0
	v_mad_i64_i32 v[98:99], s[4:5], v149, s66, v[130:131]
	global_store_short v[98:99], v100, off
	v_add_f32_e32 v98, v106, v133
	v_mul_f32_e32 v98, 0xbfb8aa3b, v98
	v_exp_f32_e32 v98, v98
	s_nop 0
	v_add_f32_e32 v98, 1.0, v98
	v_rcp_f32_e32 v98, v98
	s_nop 0
	v_cvt_pk_bf16_f32 v100, v98, s0
	v_mad_i64_i32 v[98:99], s[4:5], v150, s66, v[130:131]
	global_store_short v[98:99], v100, off
	v_add_f32_e32 v98, v107, v133
	v_mul_f32_e32 v98, 0xbfb8aa3b, v98
	v_exp_f32_e32 v98, v98
	v_mad_i64_i32 v[106:107], s[4:5], v164, s66, v[140:141]
	v_add_f32_e32 v98, 1.0, v98
	v_rcp_f32_e32 v98, v98
	s_nop 0
	v_cvt_pk_bf16_f32 v100, v98, s0
	v_mad_i64_i32 v[98:99], s[4:5], v151, s66, v[130:131]
	global_store_short v[98:99], v100, off
	v_add_f32_e32 v98, v108, v133
	v_mul_f32_e32 v98, 0xbfb8aa3b, v98
	v_exp_f32_e32 v98, v98
	s_nop 0
	v_add_f32_e32 v98, 1.0, v98
	v_rcp_f32_e32 v98, v98
	s_nop 0
	v_cvt_pk_bf16_f32 v100, v98, s0
	v_mad_i64_i32 v[98:99], s[4:5], v152, s66, v[130:131]
	global_store_short v[98:99], v100, off
	v_add_f32_e32 v98, v109, v133
	v_mul_f32_e32 v98, 0xbfb8aa3b, v98
	v_exp_f32_e32 v98, v98
	v_mad_i64_i32 v[108:109], s[4:5], v163, s66, v[140:141]
	v_add_f32_e32 v98, 1.0, v98
	v_rcp_f32_e32 v98, v98
	s_nop 0
	v_cvt_pk_bf16_f32 v100, v98, s0
	v_mad_i64_i32 v[98:99], s[4:5], v153, s66, v[130:131]
	global_store_short v[98:99], v100, off
	v_add_f32_e32 v98, v110, v133
	v_mul_f32_e32 v98, 0xbfb8aa3b, v98
	v_exp_f32_e32 v98, v98
	s_nop 0
	v_add_f32_e32 v98, 1.0, v98
	v_rcp_f32_e32 v98, v98
	s_nop 0
	v_cvt_pk_bf16_f32 v100, v98, s0
	v_mad_i64_i32 v[98:99], s[4:5], v154, s66, v[130:131]
	global_store_short v[98:99], v100, off
	v_add_f32_e32 v98, v111, v133
	v_mul_f32_e32 v98, 0xbfb8aa3b, v98
	v_exp_f32_e32 v98, v98
	v_mad_i64_i32 v[110:111], s[4:5], v162, s66, v[140:141]
	v_add_f32_e32 v98, 1.0, v98
	v_rcp_f32_e32 v98, v98
	s_nop 0
	v_cvt_pk_bf16_f32 v100, v98, s0
	v_mad_i64_i32 v[98:99], s[4:5], v155, s66, v[130:131]
	global_store_short v[98:99], v100, off
	v_add_f32_e32 v98, v112, v133
; __device__ __forceinline__ uint32_t pk2(float lo, float hi) { typedef float f2 __attribute__((ext_vector_type(2))); const f2 v = {lo, hi}; return __builtin_bit_cast(uint32_t, __builtin_convertvector(v, bf16x2_t)); }
; __device__ __forceinline__ float sigmf(float x) { return __builtin_amdgcn_rcpf(1.f + __expf(-x)); }
; __device__ __forceinline__ void phase_gate(const Params& p, int l, int b, unsigned char* lds) {
;     ...
; #pragma unroll
;         for (int ni = 0; ni < 4; ++ni) {
;             const int n = pn * 256 + wc * 128 + ni * 32 + r;
;             const float bias = bg[n];
; #pragma unroll
;             for (int mi = 0; mi < 2; ++mi)
; #pragma unroll
;                 for (int reg = 0; reg < 16; ++reg) {
;                     const int m = pm * 128 + wr * 64 + mi * 32 + (reg & 3) + 8 * (reg >> 2) + 4 * h;
;                     G[(size_t)m * 3072 + n] = (bf16_t)(pk2(sigmf(acc[mi][ni][reg] + bias), 0.f) & 0xffff);
;                 }
;         }
	v_mul_f32_e32 v98, 0xbfb8aa3b, v98
	v_exp_f32_e32 v98, v98
	s_nop 0
	v_add_f32_e32 v98, 1.0, v98
	v_rcp_f32_e32 v98, v98
	s_nop 0
	v_cvt_pk_bf16_f32 v100, v98, s0
	v_mad_i64_i32 v[98:99], s[4:5], v156, s66, v[130:131]
	global_store_short v[98:99], v100, off
	v_add_f32_e32 v98, v113, v133
	v_mul_f32_e32 v98, 0xbfb8aa3b, v98
	v_exp_f32_e32 v98, v98
	v_mad_i64_i32 v[132:133], s[4:5], v114, s66, v[140:141]
	v_mad_i64_i32 v[112:113], s[4:5], v161, s66, v[140:141]
	v_add_f32_e32 v98, 1.0, v98
	v_rcp_f32_e32 v98, v98
	s_nop 0
	v_cvt_pk_bf16_f32 v100, v98, s0
	v_mad_i64_i32 v[98:99], s[4:5], v157, s66, v[130:131]
	global_store_short v[98:99], v100, off
	v_or_b32_e32 v98, 32, v138
	v_ashrrev_i32_e32 v99, 31, v98
	v_lshlrev_b64 v[142:143], 1, v[98:99]
	v_lshl_add_u64 v[98:99], v[134:135], 0, v[142:143]
	global_store_short v[98:99], v82, off
	v_add_f32_e32 v82, v83, v166
	v_mul_f32_e32 v82, 0xbfb8aa3b, v82
	v_exp_f32_e32 v82, v82
	v_mad_i64_i32 v[130:131], s[4:5], v115, s66, v[140:141]
	v_mad_i64_i32 v[114:115], s[4:5], v160, s66, v[140:141]
	v_add_f32_e32 v82, 1.0, v82
	v_rcp_f32_e32 v82, v82
	v_mad_i64_i32 v[100:101], s[4:5], v139, s66, v[140:141]
	v_cvt_pk_bf16_f32 v98, v82, s0
	v_lshl_add_u64 v[82:83], v[132:133], 0, v[142:143]
	global_store_short v[82:83], v98, off
	v_add_f32_e32 v82, v84, v166
	v_mul_f32_e32 v82, 0xbfb8aa3b, v82
	v_exp_f32_e32 v82, v82
	v_mad_i64_i32 v[98:99], s[4:5], v144, s66, v[140:141]
	v_add_f32_e32 v82, 1.0, v82
	v_rcp_f32_e32 v82, v82
	s_nop 0
	v_cvt_pk_bf16_f32 v84, v82, s0
	v_lshl_add_u64 v[82:83], v[130:131], 0, v[142:143]
	global_store_short v[82:83], v84, off
	v_add_f32_e32 v82, v85, v166
	v_mul_f32_e32 v82, 0xbfb8aa3b, v82
	v_exp_f32_e32 v82, v82
	s_nop 0
	v_add_f32_e32 v82, 1.0, v82
	v_rcp_f32_e32 v82, v82
	s_nop 0
	v_cvt_pk_bf16_f32 v84, v82, s0
	v_lshl_add_u64 v[82:83], v[128:129], 0, v[142:143]
	global_store_short v[82:83], v84, off
	v_add_f32_e32 v82, v86, v166
	v_mul_f32_e32 v82, 0xbfb8aa3b, v82
	v_exp_f32_e32 v82, v82
	s_nop 0
	v_add_f32_e32 v82, 1.0, v82
	v_rcp_f32_e32 v82, v82
	s_nop 0
	v_cvt_pk_bf16_f32 v84, v82, s0
	v_lshl_add_u64 v[82:83], v[126:127], 0, v[142:143]
	global_store_short v[82:83], v84, off
	v_add_f32_e32 v82, v87, v166
	v_mul_f32_e32 v82, 0xbfb8aa3b, v82
	v_exp_f32_e32 v82, v82
	v_mad_i64_i32 v[86:87], s[4:5], v150, s66, v[140:141]
	v_add_f32_e32 v82, 1.0, v82
	v_rcp_f32_e32 v82, v82
	s_nop 0
	v_cvt_pk_bf16_f32 v84, v82, s0
	v_lshl_add_u64 v[82:83], v[124:125], 0, v[142:143]
	global_store_short v[82:83], v84, off
	v_add_f32_e32 v82, v88, v166
	v_mul_f32_e32 v82, 0xbfb8aa3b, v82
	v_exp_f32_e32 v82, v82
	s_nop 0
	v_add_f32_e32 v82, 1.0, v82
	v_rcp_f32_e32 v82, v82
	s_nop 0
	v_cvt_pk_bf16_f32 v84, v82, s0
	v_lshl_add_u64 v[82:83], v[122:123], 0, v[142:143]
	global_store_short v[82:83], v84, off
	v_add_f32_e32 v82, v89, v166
	v_mul_f32_e32 v82, 0xbfb8aa3b, v82
	v_exp_f32_e32 v82, v82
	v_mad_i64_i32 v[88:89], s[4:5], v149, s66, v[140:141]
	v_add_f32_e32 v82, 1.0, v82
	v_rcp_f32_e32 v82, v82
	s_nop 0
	v_cvt_pk_bf16_f32 v84, v82, s0
	v_lshl_add_u64 v[82:83], v[120:121], 0, v[142:143]
	global_store_short v[82:83], v84, off
	v_add_f32_e32 v82, v90, v166
	v_mul_f32_e32 v82, 0xbfb8aa3b, v82
	v_exp_f32_e32 v82, v82
	s_nop 0
	v_add_f32_e32 v82, 1.0, v82
	v_rcp_f32_e32 v82, v82
	s_nop 0
	v_cvt_pk_bf16_f32 v84, v82, s0
	v_lshl_add_u64 v[82:83], v[118:119], 0, v[142:143]
	global_store_short v[82:83], v84, off
	v_add_f32_e32 v82, v91, v166
	v_mul_f32_e32 v82, 0xbfb8aa3b, v82
	v_exp_f32_e32 v82, v82
	v_mad_i64_i32 v[90:91], s[4:5], v148, s66, v[140:141]
	v_add_f32_e32 v82, 1.0, v82
	v_rcp_f32_e32 v82, v82
	s_nop 0
	v_cvt_pk_bf16_f32 v84, v82, s0
	v_lshl_add_u64 v[82:83], v[116:117], 0, v[142:143]
	global_store_short v[82:83], v84, off
	v_add_f32_e32 v82, v92, v166
	v_mul_f32_e32 v82, 0xbfb8aa3b, v82
	v_exp_f32_e32 v82, v82
	s_nop 0
	v_add_f32_e32 v82, 1.0, v82
	v_rcp_f32_e32 v82, v82
	s_nop 0
	v_cvt_pk_bf16_f32 v84, v82, s0
	v_lshl_add_u64 v[82:83], v[114:115], 0, v[142:143]
	global_store_short v[82:83], v84, off
	v_add_f32_e32 v82, v93, v166
	v_mul_f32_e32 v82, 0xbfb8aa3b, v82
	v_exp_f32_e32 v82, v82
	v_mad_i64_i32 v[92:93], s[4:5], v147, s66, v[140:141]
	v_add_f32_e32 v82, 1.0, v82
	v_rcp_f32_e32 v82, v82
	s_nop 0
	v_cvt_pk_bf16_f32 v84, v82, s0
	v_lshl_add_u64 v[82:83], v[112:113], 0, v[142:143]
	global_store_short v[82:83], v84, off
	v_add_f32_e32 v82, v94, v166
	v_mul_f32_e32 v82, 0xbfb8aa3b, v82
	v_exp_f32_e32 v82, v82
	s_nop 0
	v_add_f32_e32 v82, 1.0, v82
	v_rcp_f32_e32 v82, v82
	s_nop 0
	v_cvt_pk_bf16_f32 v84, v82, s0
	v_lshl_add_u64 v[82:83], v[110:111], 0, v[142:143]
	global_store_short v[82:83], v84, off
	v_add_f32_e32 v82, v95, v166
	v_mul_f32_e32 v82, 0xbfb8aa3b, v82
	v_exp_f32_e32 v82, v82
	v_mad_i64_i32 v[94:95], s[4:5], v146, s66, v[140:141]
	v_add_f32_e32 v82, 1.0, v82
	v_rcp_f32_e32 v82, v82
	s_nop 0
	v_cvt_pk_bf16_f32 v84, v82, s0
	v_lshl_add_u64 v[82:83], v[108:109], 0, v[142:143]
	global_store_short v[82:83], v84, off
	v_add_f32_e32 v82, v96, v166
	v_mul_f32_e32 v82, 0xbfb8aa3b, v82
	v_exp_f32_e32 v82, v82
	s_nop 0
	v_add_f32_e32 v82, 1.0, v82
	v_rcp_f32_e32 v82, v82
	s_nop 0
	v_cvt_pk_bf16_f32 v84, v82, s0
	v_lshl_add_u64 v[82:83], v[106:107], 0, v[142:143]
	global_store_short v[82:83], v84, off
	v_add_f32_e32 v82, v97, v166
	v_mul_f32_e32 v82, 0xbfb8aa3b, v82
	v_exp_f32_e32 v82, v82
	v_mad_i64_i32 v[96:97], s[4:5], v145, s66, v[140:141]
	v_add_f32_e32 v82, 1.0, v82
	v_rcp_f32_e32 v82, v82
	s_nop 0
	v_cvt_pk_bf16_f32 v84, v82, s0
	v_lshl_add_u64 v[82:83], v[104:105], 0, v[142:143]
	global_store_short v[82:83], v84, off
	v_lshl_add_u64 v[82:83], v[102:103], 0, v[142:143]
; __device__ __forceinline__ uint32_t pk2(float lo, float hi) { typedef float f2 __attribute__((ext_vector_type(2))); const f2 v = {lo, hi}; return __builtin_bit_cast(uint32_t, __builtin_convertvector(v, bf16x2_t)); }
; __device__ __forceinline__ float sigmf(float x) { return __builtin_amdgcn_rcpf(1.f + __expf(-x)); }
; __device__ __forceinline__ void phase_gate(const Params& p, int l, int b, unsigned char* lds) {
;     ...
; #pragma unroll
;         for (int ni = 0; ni < 4; ++ni) {
;             const int n = pn * 256 + wc * 128 + ni * 32 + r;
;             const float bias = bg[n];
; #pragma unroll
;             for (int mi = 0; mi < 2; ++mi)
; #pragma unroll
;                 for (int reg = 0; reg < 16; ++reg) {
;                     const int m = pm * 128 + wr * 64 + mi * 32 + (reg & 3) + 8 * (reg >> 2) + 4 * h;
;                     G[(size_t)m * 3072 + n] = (bf16_t)(pk2(sigmf(acc[mi][ni][reg] + bias), 0.f) & 0xffff);
;                 }
;         }
	global_store_short v[82:83], v66, off
	v_lshl_add_u64 v[66:67], v[100:101], 0, v[142:143]
	global_store_short v[66:67], v0, off
	v_add_f32_e32 v0, v68, v166
	v_mul_f32_e32 v0, 0xbfb8aa3b, v0
	v_exp_f32_e32 v0, v0
	v_lshl_add_u64 v[66:67], v[98:99], 0, v[142:143]
	v_mad_i64_i32 v[84:85], s[4:5], v151, s66, v[140:141]
	v_add_f32_e32 v0, 1.0, v0
	v_rcp_f32_e32 v0, v0
	v_mad_i64_i32 v[82:83], s[4:5], v152, s66, v[140:141]
	v_cvt_pk_bf16_f32 v0, v0, s0
	global_store_short v[66:67], v0, off
	v_add_f32_e32 v0, v69, v166
	v_mul_f32_e32 v0, 0xbfb8aa3b, v0
	v_exp_f32_e32 v0, v0
	v_lshl_add_u64 v[66:67], v[96:97], 0, v[142:143]
	v_mad_i64_i32 v[68:69], s[4:5], v156, s66, v[140:141]
	v_add_f32_e32 v0, 1.0, v0
	v_rcp_f32_e32 v0, v0
	s_nop 0
	v_cvt_pk_bf16_f32 v0, v0, s0
	global_store_short v[66:67], v0, off
	v_add_f32_e32 v0, v70, v166
	v_mul_f32_e32 v0, 0xbfb8aa3b, v0
	v_exp_f32_e32 v0, v0
	v_lshl_add_u64 v[66:67], v[94:95], 0, v[142:143]
	v_add_f32_e32 v0, 1.0, v0
	v_rcp_f32_e32 v0, v0
	s_nop 0
	v_cvt_pk_bf16_f32 v0, v0, s0
	global_store_short v[66:67], v0, off
	v_add_f32_e32 v0, v71, v166
	v_mul_f32_e32 v0, 0xbfb8aa3b, v0
	v_exp_f32_e32 v0, v0
	v_lshl_add_u64 v[66:67], v[92:93], 0, v[142:143]
	v_mad_i64_i32 v[70:71], s[4:5], v155, s66, v[140:141]
	v_add_f32_e32 v0, 1.0, v0
	v_rcp_f32_e32 v0, v0
	s_nop 0
	v_cvt_pk_bf16_f32 v0, v0, s0
	global_store_short v[66:67], v0, off
	v_add_f32_e32 v0, v72, v166
	v_mul_f32_e32 v0, 0xbfb8aa3b, v0
	v_exp_f32_e32 v0, v0
	v_lshl_add_u64 v[66:67], v[90:91], 0, v[142:143]
	v_add_f32_e32 v0, 1.0, v0
	v_rcp_f32_e32 v0, v0
	s_nop 0
	v_cvt_pk_bf16_f32 v0, v0, s0
	global_store_short v[66:67], v0, off
	v_add_f32_e32 v0, v73, v166
	v_mul_f32_e32 v0, 0xbfb8aa3b, v0
	v_exp_f32_e32 v0, v0
	v_lshl_add_u64 v[66:67], v[88:89], 0, v[142:143]
	v_mad_i64_i32 v[72:73], s[4:5], v154, s66, v[140:141]
	v_add_f32_e32 v0, 1.0, v0
	v_rcp_f32_e32 v0, v0
	s_nop 0
	v_cvt_pk_bf16_f32 v0, v0, s0
	global_store_short v[66:67], v0, off
	v_add_f32_e32 v0, v74, v166
	v_mul_f32_e32 v0, 0xbfb8aa3b, v0
	v_exp_f32_e32 v0, v0
	v_lshl_add_u64 v[66:67], v[86:87], 0, v[142:143]
	v_add_f32_e32 v0, 1.0, v0
	v_rcp_f32_e32 v0, v0
	s_nop 0
	v_cvt_pk_bf16_f32 v0, v0, s0
	global_store_short v[66:67], v0, off
	v_add_f32_e32 v0, v75, v166
	v_mul_f32_e32 v0, 0xbfb8aa3b, v0
	v_exp_f32_e32 v0, v0
	v_lshl_add_u64 v[66:67], v[84:85], 0, v[142:143]
	v_mad_i64_i32 v[74:75], s[4:5], v153, s66, v[140:141]
	v_add_f32_e32 v0, 1.0, v0
	v_rcp_f32_e32 v0, v0
	s_nop 0
	v_cvt_pk_bf16_f32 v0, v0, s0
	global_store_short v[66:67], v0, off
	v_add_f32_e32 v0, v76, v166
	v_mul_f32_e32 v0, 0xbfb8aa3b, v0
	v_exp_f32_e32 v0, v0
	v_lshl_add_u64 v[66:67], v[82:83], 0, v[142:143]
	v_add_f32_e32 v0, 1.0, v0
	v_rcp_f32_e32 v0, v0
	s_nop 0
	v_cvt_pk_bf16_f32 v0, v0, s0
	global_store_short v[66:67], v0, off
	v_add_f32_e32 v0, v77, v166
	v_mul_f32_e32 v0, 0xbfb8aa3b, v0
	v_exp_f32_e32 v0, v0
	v_lshl_add_u64 v[66:67], v[74:75], 0, v[142:143]
	v_add_f32_e32 v0, 1.0, v0
	v_rcp_f32_e32 v0, v0
	s_nop 0
	v_cvt_pk_bf16_f32 v0, v0, s0
	global_store_short v[66:67], v0, off
	v_add_f32_e32 v0, v78, v166
	v_mul_f32_e32 v0, 0xbfb8aa3b, v0
	v_exp_f32_e32 v0, v0
	v_lshl_add_u64 v[66:67], v[72:73], 0, v[142:143]
	v_add_f32_e32 v0, 1.0, v0
	v_rcp_f32_e32 v0, v0
	s_nop 0
	v_cvt_pk_bf16_f32 v0, v0, s0
	global_store_short v[66:67], v0, off
	v_add_f32_e32 v0, v79, v166
	v_mul_f32_e32 v0, 0xbfb8aa3b, v0
	v_exp_f32_e32 v0, v0
	v_lshl_add_u64 v[66:67], v[70:71], 0, v[142:143]
	v_add_f32_e32 v0, 1.0, v0
	v_rcp_f32_e32 v0, v0
	s_nop 0
	v_cvt_pk_bf16_f32 v0, v0, s0
	global_store_short v[66:67], v0, off
	v_add_f32_e32 v0, v80, v166
	v_mul_f32_e32 v0, 0xbfb8aa3b, v0
	v_exp_f32_e32 v0, v0
	v_lshl_add_u64 v[66:67], v[68:69], 0, v[142:143]
	v_add_f32_e32 v0, 1.0, v0
	v_rcp_f32_e32 v0, v0
	s_nop 0
	v_cvt_pk_bf16_f32 v0, v0, s0
	global_store_short v[66:67], v0, off
	v_add_f32_e32 v0, v81, v166
	v_mul_f32_e32 v0, 0xbfb8aa3b, v0
	v_exp_f32_e32 v0, v0
	v_mad_i64_i32 v[66:67], s[4:5], v157, s66, v[140:141]
	v_lshl_add_u64 v[76:77], v[66:67], 0, v[142:143]
	v_add_f32_e32 v0, 1.0, v0
	v_rcp_f32_e32 v0, v0
	s_mul_i32 s4, s14, s11
	s_add_i32 s4, s4, s95
	s_cmpk_gt_u32 s4, 0xbf
	v_cvt_pk_bf16_f32 v0, v0, s0
	global_store_short v[76:77], v0, off
	v_or_b32_e32 v76, 64, v138
	v_ashrrev_i32_e32 v77, 31, v76
	v_lshlrev_b64 v[76:77], 1, v[76:77]
	v_lshl_add_u64 v[78:79], v[134:135], 0, v[76:77]
	s_waitcnt vmcnt(63)
; __device__ __forceinline__ uint32_t pk2(float lo, float hi) { typedef float f2 __attribute__((ext_vector_type(2))); const f2 v = {lo, hi}; return __builtin_bit_cast(uint32_t, __builtin_convertvector(v, bf16x2_t)); }
; __device__ __forceinline__ float sigmf(float x) { return __builtin_amdgcn_rcpf(1.f + __expf(-x)); }
; __device__ __forceinline__ void phase_gate(const Params& p, int l, int b, unsigned char* lds) {
;     ...
; #pragma unroll
;         for (int ni = 0; ni < 4; ++ni) {
;             const int n = pn * 256 + wc * 128 + ni * 32 + r;
;             const float bias = bg[n];
; #pragma unroll
;             for (int mi = 0; mi < 2; ++mi)
; #pragma unroll
;                 for (int reg = 0; reg < 16; ++reg) {
;                     const int m = pm * 128 + wr * 64 + mi * 32 + (reg & 3) + 8 * (reg >> 2) + 4 * h;
;                     G[(size_t)m * 3072 + n] = (bf16_t)(pk2(sigmf(acc[mi][ni][reg] + bias), 0.f) & 0xffff);
;                 }
;         }
	v_add_f32_e32 v50, v50, v200
	v_mul_f32_e32 v50, 0xbfb8aa3b, v50
	v_exp_f32_e32 v50, v50
	v_add_f32_e32 v34, v34, v200
	v_mul_f32_e32 v34, 0xbfb8aa3b, v34
	v_exp_f32_e32 v34, v34
	v_add_f32_e32 v50, 1.0, v50
	v_rcp_f32_e32 v50, v50
	v_add_f32_e32 v34, 1.0, v34
	v_rcp_f32_e32 v34, v34
	v_cvt_pk_bf16_f32 v50, v50, s0
	global_store_short v[78:79], v50, off
	v_add_f32_e32 v50, v51, v200
	v_mul_f32_e32 v50, 0xbfb8aa3b, v50
	v_exp_f32_e32 v50, v50
	v_cvt_pk_bf16_f32 v34, v34, s0
	v_add_f32_e32 v50, 1.0, v50
	v_rcp_f32_e32 v50, v50
	s_nop 0
	v_cvt_pk_bf16_f32 v78, v50, s0
	v_lshl_add_u64 v[50:51], v[132:133], 0, v[76:77]
	global_store_short v[50:51], v78, off
	v_add_f32_e32 v50, v52, v200
	v_mul_f32_e32 v50, 0xbfb8aa3b, v50
	v_exp_f32_e32 v50, v50
	s_nop 0
	v_add_f32_e32 v50, 1.0, v50
	v_rcp_f32_e32 v50, v50
	s_nop 0
	v_cvt_pk_bf16_f32 v52, v50, s0
	v_lshl_add_u64 v[50:51], v[130:131], 0, v[76:77]
	global_store_short v[50:51], v52, off
	v_add_f32_e32 v50, v53, v200
	v_mul_f32_e32 v50, 0xbfb8aa3b, v50
	v_exp_f32_e32 v50, v50
	s_nop 0
	v_add_f32_e32 v50, 1.0, v50
	v_rcp_f32_e32 v50, v50
	s_nop 0
	v_cvt_pk_bf16_f32 v52, v50, s0
	v_lshl_add_u64 v[50:51], v[128:129], 0, v[76:77]
	global_store_short v[50:51], v52, off
	v_add_f32_e32 v50, v54, v200
	v_mul_f32_e32 v50, 0xbfb8aa3b, v50
	v_exp_f32_e32 v50, v50
	s_nop 0
	v_add_f32_e32 v50, 1.0, v50
	v_rcp_f32_e32 v50, v50
	s_nop 0
	v_cvt_pk_bf16_f32 v52, v50, s0
	v_lshl_add_u64 v[50:51], v[126:127], 0, v[76:77]
	global_store_short v[50:51], v52, off
	v_add_f32_e32 v50, v55, v200
	v_mul_f32_e32 v50, 0xbfb8aa3b, v50
	v_exp_f32_e32 v50, v50
	s_nop 0
	v_add_f32_e32 v50, 1.0, v50
	v_rcp_f32_e32 v50, v50
	s_nop 0
	v_cvt_pk_bf16_f32 v52, v50, s0
	v_lshl_add_u64 v[50:51], v[124:125], 0, v[76:77]
	global_store_short v[50:51], v52, off
	v_add_f32_e32 v50, v56, v200
	v_mul_f32_e32 v50, 0xbfb8aa3b, v50
	v_exp_f32_e32 v50, v50
	s_nop 0
	v_add_f32_e32 v50, 1.0, v50
	v_rcp_f32_e32 v50, v50
	s_nop 0
	v_cvt_pk_bf16_f32 v52, v50, s0
	v_lshl_add_u64 v[50:51], v[122:123], 0, v[76:77]
	global_store_short v[50:51], v52, off
	v_add_f32_e32 v50, v57, v200
	v_mul_f32_e32 v50, 0xbfb8aa3b, v50
	v_exp_f32_e32 v50, v50
	s_nop 0
	v_add_f32_e32 v50, 1.0, v50
	v_rcp_f32_e32 v50, v50
	s_nop 0
	v_cvt_pk_bf16_f32 v52, v50, s0
	v_lshl_add_u64 v[50:51], v[120:121], 0, v[76:77]
	global_store_short v[50:51], v52, off
	v_add_f32_e32 v50, v58, v200
	v_mul_f32_e32 v50, 0xbfb8aa3b, v50
	v_exp_f32_e32 v50, v50
	s_nop 0
	v_add_f32_e32 v50, 1.0, v50
	v_rcp_f32_e32 v50, v50
	s_nop 0
	v_cvt_pk_bf16_f32 v52, v50, s0
	v_lshl_add_u64 v[50:51], v[118:119], 0, v[76:77]
	global_store_short v[50:51], v52, off
	v_add_f32_e32 v50, v59, v200
	v_mul_f32_e32 v50, 0xbfb8aa3b, v50
	v_exp_f32_e32 v50, v50
	s_nop 0
	v_add_f32_e32 v50, 1.0, v50
	v_rcp_f32_e32 v50, v50
	s_nop 0
	v_cvt_pk_bf16_f32 v52, v50, s0
	v_lshl_add_u64 v[50:51], v[116:117], 0, v[76:77]
	global_store_short v[50:51], v52, off
	v_add_f32_e32 v50, v60, v200
	v_mul_f32_e32 v50, 0xbfb8aa3b, v50
	v_exp_f32_e32 v50, v50
	s_nop 0
	v_add_f32_e32 v50, 1.0, v50
	v_rcp_f32_e32 v50, v50
	s_nop 0
	v_cvt_pk_bf16_f32 v52, v50, s0
	v_lshl_add_u64 v[50:51], v[114:115], 0, v[76:77]
	global_store_short v[50:51], v52, off
	v_add_f32_e32 v50, v61, v200
	v_mul_f32_e32 v50, 0xbfb8aa3b, v50
	v_exp_f32_e32 v50, v50
	s_nop 0
	v_add_f32_e32 v50, 1.0, v50
	v_rcp_f32_e32 v50, v50
	s_nop 0
	v_cvt_pk_bf16_f32 v52, v50, s0
	v_lshl_add_u64 v[50:51], v[112:113], 0, v[76:77]
	global_store_short v[50:51], v52, off
	v_add_f32_e32 v50, v62, v200
	v_mul_f32_e32 v50, 0xbfb8aa3b, v50
	v_exp_f32_e32 v50, v50
	s_nop 0
	v_add_f32_e32 v50, 1.0, v50
	v_rcp_f32_e32 v50, v50
	s_nop 0
	v_cvt_pk_bf16_f32 v52, v50, s0
	v_lshl_add_u64 v[50:51], v[110:111], 0, v[76:77]
	global_store_short v[50:51], v52, off
	v_add_f32_e32 v50, v63, v200
	v_mul_f32_e32 v50, 0xbfb8aa3b, v50
	v_exp_f32_e32 v50, v50
	s_nop 0
	v_add_f32_e32 v50, 1.0, v50
	v_rcp_f32_e32 v50, v50
	s_nop 0
	v_cvt_pk_bf16_f32 v52, v50, s0
	v_lshl_add_u64 v[50:51], v[108:109], 0, v[76:77]
	global_store_short v[50:51], v52, off
	v_add_f32_e32 v50, v64, v200
	v_mul_f32_e32 v50, 0xbfb8aa3b, v50
	v_exp_f32_e32 v50, v50
	s_nop 0
	v_add_f32_e32 v50, 1.0, v50
	v_rcp_f32_e32 v50, v50
	s_nop 0
	v_cvt_pk_bf16_f32 v52, v50, s0
	v_lshl_add_u64 v[50:51], v[106:107], 0, v[76:77]
	global_store_short v[50:51], v52, off
	v_add_f32_e32 v50, v65, v200
	v_mul_f32_e32 v50, 0xbfb8aa3b, v50
	v_exp_f32_e32 v50, v50
	s_nop 0
	v_add_f32_e32 v50, 1.0, v50
	v_rcp_f32_e32 v50, v50
	s_nop 0
	v_cvt_pk_bf16_f32 v52, v50, s0
	v_lshl_add_u64 v[50:51], v[104:105], 0, v[76:77]
	global_store_short v[50:51], v52, off
	v_lshl_add_u64 v[50:51], v[102:103], 0, v[76:77]
	global_store_short v[50:51], v34, off
	v_add_f32_e32 v34, v35, v200
	v_mul_f32_e32 v34, 0xbfb8aa3b, v34
	v_exp_f32_e32 v34, v34
	s_nop 0
	v_add_f32_e32 v34, 1.0, v34
	v_rcp_f32_e32 v34, v34
	s_nop 0
	v_cvt_pk_bf16_f32 v50, v34, s0
	v_lshl_add_u64 v[34:35], v[100:101], 0, v[76:77]
	global_store_short v[34:35], v50, off
	v_add_f32_e32 v34, v36, v200
	v_mul_f32_e32 v34, 0xbfb8aa3b, v34
	v_exp_f32_e32 v34, v34
	s_nop 0
	v_add_f32_e32 v34, 1.0, v34
	v_rcp_f32_e32 v34, v34
	s_nop 0
	v_cvt_pk_bf16_f32 v36, v34, s0
	v_lshl_add_u64 v[34:35], v[98:99], 0, v[76:77]
	global_store_short v[34:35], v36, off
	v_add_f32_e32 v34, v37, v200
	v_mul_f32_e32 v34, 0xbfb8aa3b, v34
	v_exp_f32_e32 v34, v34
	s_nop 0
	v_add_f32_e32 v34, 1.0, v34
	v_rcp_f32_e32 v34, v34
	s_nop 0
	v_cvt_pk_bf16_f32 v36, v34, s0
	v_lshl_add_u64 v[34:35], v[96:97], 0, v[76:77]
	global_store_short v[34:35], v36, off
	v_add_f32_e32 v34, v38, v200
	v_mul_f32_e32 v34, 0xbfb8aa3b, v34
	v_exp_f32_e32 v34, v34
	s_nop 0
; __device__ __forceinline__ uint32_t pk2(float lo, float hi) { typedef float f2 __attribute__((ext_vector_type(2))); const f2 v = {lo, hi}; return __builtin_bit_cast(uint32_t, __builtin_convertvector(v, bf16x2_t)); }
; __device__ __forceinline__ float sigmf(float x) { return __builtin_amdgcn_rcpf(1.f + __expf(-x)); }
; __device__ __forceinline__ void phase_gate(const Params& p, int l, int b, unsigned char* lds) {
;     ...
; #pragma unroll
;         for (int ni = 0; ni < 4; ++ni) {
;             const int n = pn * 256 + wc * 128 + ni * 32 + r;
;             const float bias = bg[n];
; #pragma unroll
;             for (int mi = 0; mi < 2; ++mi)
; #pragma unroll
;                 for (int reg = 0; reg < 16; ++reg) {
;                     const int m = pm * 128 + wr * 64 + mi * 32 + (reg & 3) + 8 * (reg >> 2) + 4 * h;
;                     G[(size_t)m * 3072 + n] = (bf16_t)(pk2(sigmf(acc[mi][ni][reg] + bias), 0.f) & 0xffff);
;                 }
;         }
	v_add_f32_e32 v34, 1.0, v34
	v_rcp_f32_e32 v34, v34
	s_nop 0
	v_cvt_pk_bf16_f32 v36, v34, s0
	v_lshl_add_u64 v[34:35], v[94:95], 0, v[76:77]
	global_store_short v[34:35], v36, off
	v_add_f32_e32 v34, v39, v200
	v_mul_f32_e32 v34, 0xbfb8aa3b, v34
	v_exp_f32_e32 v34, v34
	s_nop 0
	v_add_f32_e32 v34, 1.0, v34
	v_rcp_f32_e32 v34, v34
	s_nop 0
	v_cvt_pk_bf16_f32 v36, v34, s0
	v_lshl_add_u64 v[34:35], v[92:93], 0, v[76:77]
	global_store_short v[34:35], v36, off
	v_add_f32_e32 v34, v40, v200
	v_mul_f32_e32 v34, 0xbfb8aa3b, v34
	v_exp_f32_e32 v34, v34
	s_nop 0
	v_add_f32_e32 v34, 1.0, v34
	v_rcp_f32_e32 v34, v34
	s_nop 0
	v_cvt_pk_bf16_f32 v36, v34, s0
	v_lshl_add_u64 v[34:35], v[90:91], 0, v[76:77]
	global_store_short v[34:35], v36, off
	v_add_f32_e32 v34, v41, v200
	v_mul_f32_e32 v34, 0xbfb8aa3b, v34
	v_exp_f32_e32 v34, v34
	s_nop 0
	v_add_f32_e32 v34, 1.0, v34
	v_rcp_f32_e32 v34, v34
	s_nop 0
	v_cvt_pk_bf16_f32 v36, v34, s0
	v_lshl_add_u64 v[34:35], v[88:89], 0, v[76:77]
	global_store_short v[34:35], v36, off
	v_add_f32_e32 v34, v42, v200
	v_mul_f32_e32 v34, 0xbfb8aa3b, v34
	v_exp_f32_e32 v34, v34
	s_nop 0
	v_add_f32_e32 v34, 1.0, v34
	v_rcp_f32_e32 v34, v34
	s_nop 0
	v_cvt_pk_bf16_f32 v36, v34, s0
	v_lshl_add_u64 v[34:35], v[86:87], 0, v[76:77]
	global_store_short v[34:35], v36, off
	v_add_f32_e32 v34, v43, v200
	v_mul_f32_e32 v34, 0xbfb8aa3b, v34
	v_exp_f32_e32 v34, v34
	s_nop 0
	v_add_f32_e32 v34, 1.0, v34
	v_rcp_f32_e32 v34, v34
	s_nop 0
	v_cvt_pk_bf16_f32 v36, v34, s0
	v_lshl_add_u64 v[34:35], v[84:85], 0, v[76:77]
	global_store_short v[34:35], v36, off
	v_add_f32_e32 v34, v44, v200
	v_mul_f32_e32 v34, 0xbfb8aa3b, v34
	v_exp_f32_e32 v34, v34
	s_nop 0
	v_add_f32_e32 v34, 1.0, v34
	v_rcp_f32_e32 v34, v34
	s_nop 0
	v_cvt_pk_bf16_f32 v36, v34, s0
	v_lshl_add_u64 v[34:35], v[82:83], 0, v[76:77]
	global_store_short v[34:35], v36, off
	v_add_f32_e32 v34, v45, v200
	v_mul_f32_e32 v34, 0xbfb8aa3b, v34
	v_exp_f32_e32 v34, v34
	s_nop 0
	v_add_f32_e32 v34, 1.0, v34
	v_rcp_f32_e32 v34, v34
	s_nop 0
	v_cvt_pk_bf16_f32 v36, v34, s0
	v_lshl_add_u64 v[34:35], v[74:75], 0, v[76:77]
	global_store_short v[34:35], v36, off
	v_add_f32_e32 v34, v46, v200
	v_mul_f32_e32 v34, 0xbfb8aa3b, v34
	v_exp_f32_e32 v34, v34
	s_nop 0
	v_add_f32_e32 v34, 1.0, v34
	v_rcp_f32_e32 v34, v34
	s_nop 0
	v_cvt_pk_bf16_f32 v36, v34, s0
	v_lshl_add_u64 v[34:35], v[72:73], 0, v[76:77]
	global_store_short v[34:35], v36, off
	v_add_f32_e32 v34, v47, v200
	v_mul_f32_e32 v34, 0xbfb8aa3b, v34
	v_exp_f32_e32 v34, v34
	s_nop 0
	v_add_f32_e32 v34, 1.0, v34
	v_rcp_f32_e32 v34, v34
	s_nop 0
	v_cvt_pk_bf16_f32 v36, v34, s0
	v_lshl_add_u64 v[34:35], v[70:71], 0, v[76:77]
	global_store_short v[34:35], v36, off
	v_add_f32_e32 v34, v48, v200
	v_mul_f32_e32 v34, 0xbfb8aa3b, v34
	v_add_f32_e32 v0, v49, v200
	v_exp_f32_e32 v34, v34
	v_mul_f32_e32 v0, 0xbfb8aa3b, v0
	v_exp_f32_e32 v0, v0
	v_add_f32_e32 v34, 1.0, v34
	v_rcp_f32_e32 v34, v34
	v_add_f32_e32 v0, 1.0, v0
	v_rcp_f32_e32 v0, v0
	v_cvt_pk_bf16_f32 v36, v34, s0
	v_lshl_add_u64 v[34:35], v[68:69], 0, v[76:77]
	global_store_short v[34:35], v36, off
	v_cvt_pk_bf16_f32 v0, v0, s0
	v_lshl_add_u64 v[34:35], v[66:67], 0, v[76:77]
	global_store_short v[34:35], v0, off
	v_or_b32_e32 v34, 0x60, v138
	v_ashrrev_i32_e32 v35, 31, v34
	v_lshlrev_b64 v[34:35], 1, v[34:35]
	v_lshl_add_u64 v[36:37], v[134:135], 0, v[34:35]
	s_waitcnt vmcnt(63)
	v_add_f32_e32 v18, v18, v201
	v_mul_f32_e32 v18, 0xbfb8aa3b, v18
	v_exp_f32_e32 v18, v18
	v_add_f32_e32 v2, v2, v201
	v_mul_f32_e32 v2, 0xbfb8aa3b, v2
	v_exp_f32_e32 v2, v2
	v_add_f32_e32 v18, 1.0, v18
	v_rcp_f32_e32 v18, v18
	v_add_f32_e32 v2, 1.0, v2
	v_rcp_f32_e32 v2, v2
	v_cvt_pk_bf16_f32 v18, v18, s0
	global_store_short v[36:37], v18, off
	v_add_f32_e32 v18, v19, v201
	v_mul_f32_e32 v18, 0xbfb8aa3b, v18
	v_exp_f32_e32 v18, v18
	v_cvt_pk_bf16_f32 v2, v2, s0
	v_add_f32_e32 v18, 1.0, v18
	v_rcp_f32_e32 v18, v18
	s_nop 0
	v_cvt_pk_bf16_f32 v36, v18, s0
	v_lshl_add_u64 v[18:19], v[132:133], 0, v[34:35]
	global_store_short v[18:19], v36, off
	v_add_f32_e32 v18, v20, v201
	v_mul_f32_e32 v18, 0xbfb8aa3b, v18
	v_exp_f32_e32 v18, v18
	s_nop 0
	v_add_f32_e32 v18, 1.0, v18
	v_rcp_f32_e32 v18, v18
	s_nop 0
	v_cvt_pk_bf16_f32 v20, v18, s0
	v_lshl_add_u64 v[18:19], v[130:131], 0, v[34:35]
	global_store_short v[18:19], v20, off
	v_add_f32_e32 v18, v21, v201
	v_mul_f32_e32 v18, 0xbfb8aa3b, v18
	v_exp_f32_e32 v18, v18
	s_nop 0
	v_add_f32_e32 v18, 1.0, v18
	v_rcp_f32_e32 v18, v18
	s_nop 0
	v_cvt_pk_bf16_f32 v20, v18, s0
	v_lshl_add_u64 v[18:19], v[128:129], 0, v[34:35]
	global_store_short v[18:19], v20, off
	v_add_f32_e32 v18, v22, v201
	v_mul_f32_e32 v18, 0xbfb8aa3b, v18
	v_exp_f32_e32 v18, v18
	s_nop 0
	v_add_f32_e32 v18, 1.0, v18
	v_rcp_f32_e32 v18, v18
	s_nop 0
	v_cvt_pk_bf16_f32 v20, v18, s0
	v_lshl_add_u64 v[18:19], v[126:127], 0, v[34:35]
	global_store_short v[18:19], v20, off
	v_add_f32_e32 v18, v23, v201
	v_mul_f32_e32 v18, 0xbfb8aa3b, v18
	v_exp_f32_e32 v18, v18
	s_nop 0
	v_add_f32_e32 v18, 1.0, v18
	v_rcp_f32_e32 v18, v18
	s_nop 0
	v_cvt_pk_bf16_f32 v20, v18, s0
	v_lshl_add_u64 v[18:19], v[124:125], 0, v[34:35]
	global_store_short v[18:19], v20, off
	v_add_f32_e32 v18, v24, v201
	v_mul_f32_e32 v18, 0xbfb8aa3b, v18
	v_exp_f32_e32 v18, v18
	s_nop 0
	v_add_f32_e32 v18, 1.0, v18
	v_rcp_f32_e32 v18, v18
	s_nop 0
	v_cvt_pk_bf16_f32 v20, v18, s0
	v_lshl_add_u64 v[18:19], v[122:123], 0, v[34:35]
	global_store_short v[18:19], v20, off
	v_add_f32_e32 v18, v25, v201
	v_mul_f32_e32 v18, 0xbfb8aa3b, v18
	v_exp_f32_e32 v18, v18
	s_nop 0
	v_add_f32_e32 v18, 1.0, v18
	v_rcp_f32_e32 v18, v18
	s_nop 0
	v_cvt_pk_bf16_f32 v20, v18, s0
; __device__ __forceinline__ uint32_t pk2(float lo, float hi) { typedef float f2 __attribute__((ext_vector_type(2))); const f2 v = {lo, hi}; return __builtin_bit_cast(uint32_t, __builtin_convertvector(v, bf16x2_t)); }
; __device__ __forceinline__ float sigmf(float x) { return __builtin_amdgcn_rcpf(1.f + __expf(-x)); }
; __device__ __forceinline__ void phase_gate(const Params& p, int l, int b, unsigned char* lds) {
;     ...
; #pragma unroll
;         for (int ni = 0; ni < 4; ++ni) {
;             const int n = pn * 256 + wc * 128 + ni * 32 + r;
;             const float bias = bg[n];
; #pragma unroll
;             for (int mi = 0; mi < 2; ++mi)
; #pragma unroll
;                 for (int reg = 0; reg < 16; ++reg) {
;                     const int m = pm * 128 + wr * 64 + mi * 32 + (reg & 3) + 8 * (reg >> 2) + 4 * h;
;                     G[(size_t)m * 3072 + n] = (bf16_t)(pk2(sigmf(acc[mi][ni][reg] + bias), 0.f) & 0xffff);
;                 }
;         }
	v_lshl_add_u64 v[18:19], v[120:121], 0, v[34:35]
	global_store_short v[18:19], v20, off
	v_add_f32_e32 v18, v26, v201
	v_mul_f32_e32 v18, 0xbfb8aa3b, v18
	v_exp_f32_e32 v18, v18
	s_nop 0
	v_add_f32_e32 v18, 1.0, v18
	v_rcp_f32_e32 v18, v18
	s_nop 0
	v_cvt_pk_bf16_f32 v20, v18, s0
	v_lshl_add_u64 v[18:19], v[118:119], 0, v[34:35]
	global_store_short v[18:19], v20, off
	v_add_f32_e32 v18, v27, v201
	v_mul_f32_e32 v18, 0xbfb8aa3b, v18
	v_exp_f32_e32 v18, v18
	s_nop 0
	v_add_f32_e32 v18, 1.0, v18
	v_rcp_f32_e32 v18, v18
	s_nop 0
	v_cvt_pk_bf16_f32 v20, v18, s0
	v_lshl_add_u64 v[18:19], v[116:117], 0, v[34:35]
	global_store_short v[18:19], v20, off
	v_add_f32_e32 v18, v28, v201
	v_mul_f32_e32 v18, 0xbfb8aa3b, v18
	v_exp_f32_e32 v18, v18
	s_nop 0
	v_add_f32_e32 v18, 1.0, v18
	v_rcp_f32_e32 v18, v18
	s_nop 0
	v_cvt_pk_bf16_f32 v20, v18, s0
	v_lshl_add_u64 v[18:19], v[114:115], 0, v[34:35]
	global_store_short v[18:19], v20, off
	v_add_f32_e32 v18, v29, v201
	v_mul_f32_e32 v18, 0xbfb8aa3b, v18
	v_exp_f32_e32 v18, v18
	s_nop 0
	v_add_f32_e32 v18, 1.0, v18
	v_rcp_f32_e32 v18, v18
	s_nop 0
	v_cvt_pk_bf16_f32 v20, v18, s0
	v_lshl_add_u64 v[18:19], v[112:113], 0, v[34:35]
	global_store_short v[18:19], v20, off
	v_add_f32_e32 v18, v30, v201
	v_mul_f32_e32 v18, 0xbfb8aa3b, v18
	v_exp_f32_e32 v18, v18
	s_nop 0
	v_add_f32_e32 v18, 1.0, v18
	v_rcp_f32_e32 v18, v18
	s_nop 0
	v_cvt_pk_bf16_f32 v20, v18, s0
	v_lshl_add_u64 v[18:19], v[110:111], 0, v[34:35]
	global_store_short v[18:19], v20, off
	v_add_f32_e32 v18, v31, v201
	v_mul_f32_e32 v18, 0xbfb8aa3b, v18
	v_exp_f32_e32 v18, v18
	s_nop 0
	v_add_f32_e32 v18, 1.0, v18
	v_rcp_f32_e32 v18, v18
	s_nop 0
	v_cvt_pk_bf16_f32 v20, v18, s0
	v_lshl_add_u64 v[18:19], v[108:109], 0, v[34:35]
	global_store_short v[18:19], v20, off
	v_add_f32_e32 v18, v32, v201
	v_mul_f32_e32 v18, 0xbfb8aa3b, v18
	v_exp_f32_e32 v18, v18
	s_nop 0
	v_add_f32_e32 v18, 1.0, v18
	v_rcp_f32_e32 v18, v18
	s_nop 0
	v_cvt_pk_bf16_f32 v20, v18, s0
	v_lshl_add_u64 v[18:19], v[106:107], 0, v[34:35]
	global_store_short v[18:19], v20, off
	v_add_f32_e32 v18, v33, v201
	v_mul_f32_e32 v18, 0xbfb8aa3b, v18
	v_exp_f32_e32 v18, v18
	s_nop 0
	v_add_f32_e32 v18, 1.0, v18
	v_rcp_f32_e32 v18, v18
	s_nop 0
	v_cvt_pk_bf16_f32 v20, v18, s0
	v_lshl_add_u64 v[18:19], v[104:105], 0, v[34:35]
	global_store_short v[18:19], v20, off
	v_lshl_add_u64 v[18:19], v[102:103], 0, v[34:35]
	global_store_short v[18:19], v2, off
	v_add_f32_e32 v2, v3, v201
	v_mul_f32_e32 v2, 0xbfb8aa3b, v2
	v_exp_f32_e32 v2, v2
	s_nop 0
	v_add_f32_e32 v2, 1.0, v2
	v_rcp_f32_e32 v2, v2
	s_nop 0
	v_cvt_pk_bf16_f32 v18, v2, s0
	v_lshl_add_u64 v[2:3], v[100:101], 0, v[34:35]
	global_store_short v[2:3], v18, off
	v_add_f32_e32 v2, v4, v201
	v_mul_f32_e32 v2, 0xbfb8aa3b, v2
	v_exp_f32_e32 v2, v2
	s_nop 0
	v_add_f32_e32 v2, 1.0, v2
	v_rcp_f32_e32 v2, v2
	s_nop 0
	v_cvt_pk_bf16_f32 v4, v2, s0
	v_lshl_add_u64 v[2:3], v[98:99], 0, v[34:35]
	global_store_short v[2:3], v4, off
	v_add_f32_e32 v2, v5, v201
	v_mul_f32_e32 v2, 0xbfb8aa3b, v2
	v_exp_f32_e32 v2, v2
	s_nop 0
	v_add_f32_e32 v2, 1.0, v2
	v_rcp_f32_e32 v2, v2
	s_nop 0
	v_cvt_pk_bf16_f32 v4, v2, s0
	v_lshl_add_u64 v[2:3], v[96:97], 0, v[34:35]
	global_store_short v[2:3], v4, off
	v_add_f32_e32 v2, v6, v201
	v_mul_f32_e32 v2, 0xbfb8aa3b, v2
	v_exp_f32_e32 v2, v2
	s_nop 0
	v_add_f32_e32 v2, 1.0, v2
	v_rcp_f32_e32 v2, v2
	s_nop 0
	v_cvt_pk_bf16_f32 v4, v2, s0
	v_lshl_add_u64 v[2:3], v[94:95], 0, v[34:35]
	global_store_short v[2:3], v4, off
	v_add_f32_e32 v2, v7, v201
	v_mul_f32_e32 v2, 0xbfb8aa3b, v2
	v_exp_f32_e32 v2, v2
	s_nop 0
	v_add_f32_e32 v2, 1.0, v2
	v_rcp_f32_e32 v2, v2
	s_nop 0
	v_cvt_pk_bf16_f32 v4, v2, s0
	v_lshl_add_u64 v[2:3], v[92:93], 0, v[34:35]
	global_store_short v[2:3], v4, off
	v_add_f32_e32 v2, v8, v201
	v_mul_f32_e32 v2, 0xbfb8aa3b, v2
	v_exp_f32_e32 v2, v2
	s_nop 0
	v_add_f32_e32 v2, 1.0, v2
	v_rcp_f32_e32 v2, v2
	s_nop 0
	v_cvt_pk_bf16_f32 v4, v2, s0
	v_lshl_add_u64 v[2:3], v[90:91], 0, v[34:35]
	global_store_short v[2:3], v4, off
	v_add_f32_e32 v2, v9, v201
	v_mul_f32_e32 v2, 0xbfb8aa3b, v2
	v_exp_f32_e32 v2, v2
	s_nop 0
	v_add_f32_e32 v2, 1.0, v2
	v_rcp_f32_e32 v2, v2
	s_nop 0
	v_cvt_pk_bf16_f32 v4, v2, s0
	v_lshl_add_u64 v[2:3], v[88:89], 0, v[34:35]
	global_store_short v[2:3], v4, off
	v_add_f32_e32 v2, v10, v201
	v_mul_f32_e32 v2, 0xbfb8aa3b, v2
	v_exp_f32_e32 v2, v2
	s_nop 0
	v_add_f32_e32 v2, 1.0, v2
	v_rcp_f32_e32 v2, v2
	s_nop 0
	v_cvt_pk_bf16_f32 v4, v2, s0
	v_lshl_add_u64 v[2:3], v[86:87], 0, v[34:35]
	global_store_short v[2:3], v4, off
	v_add_f32_e32 v2, v11, v201
	v_mul_f32_e32 v2, 0xbfb8aa3b, v2
	v_exp_f32_e32 v2, v2
	s_nop 0
	v_add_f32_e32 v2, 1.0, v2
	v_rcp_f32_e32 v2, v2
	s_nop 0
	v_cvt_pk_bf16_f32 v4, v2, s0
	v_lshl_add_u64 v[2:3], v[84:85], 0, v[34:35]
	global_store_short v[2:3], v4, off
	v_add_f32_e32 v2, v12, v201
	v_mul_f32_e32 v2, 0xbfb8aa3b, v2
	v_exp_f32_e32 v2, v2
	s_nop 0
	v_add_f32_e32 v2, 1.0, v2
	v_rcp_f32_e32 v2, v2
	s_nop 0
	v_cvt_pk_bf16_f32 v4, v2, s0
	v_lshl_add_u64 v[2:3], v[82:83], 0, v[34:35]
	global_store_short v[2:3], v4, off
	v_add_f32_e32 v2, v13, v201
	v_mul_f32_e32 v2, 0xbfb8aa3b, v2
	v_exp_f32_e32 v2, v2
	s_nop 0
	v_add_f32_e32 v2, 1.0, v2
	v_rcp_f32_e32 v2, v2
	s_nop 0
	v_cvt_pk_bf16_f32 v4, v2, s0
	v_lshl_add_u64 v[2:3], v[74:75], 0, v[34:35]
	global_store_short v[2:3], v4, off
	v_add_f32_e32 v2, v14, v201
	v_mul_f32_e32 v2, 0xbfb8aa3b, v2
	v_exp_f32_e32 v2, v2
	s_nop 0
	v_add_f32_e32 v2, 1.0, v2
	v_rcp_f32_e32 v2, v2
	s_nop 0
	v_cvt_pk_bf16_f32 v4, v2, s0
	v_lshl_add_u64 v[2:3], v[72:73], 0, v[34:35]
	global_store_short v[2:3], v4, off
	v_add_f32_e32 v2, v15, v201
	v_mul_f32_e32 v2, 0xbfb8aa3b, v2
	v_exp_f32_e32 v2, v2
	s_nop 0
	v_add_f32_e32 v2, 1.0, v2
	v_rcp_f32_e32 v2, v2
	s_nop 0
	v_cvt_pk_bf16_f32 v4, v2, s0
	v_lshl_add_u64 v[2:3], v[70:71], 0, v[34:35]
	global_store_short v[2:3], v4, off
	v_add_f32_e32 v2, v16, v201
	v_mul_f32_e32 v2, 0xbfb8aa3b, v2
	v_add_f32_e32 v0, v17, v201
	v_exp_f32_e32 v2, v2
	v_mul_f32_e32 v0, 0xbfb8aa3b, v0
	v_exp_f32_e32 v0, v0
	v_add_f32_e32 v2, 1.0, v2
	v_rcp_f32_e32 v2, v2
	v_add_f32_e32 v0, 1.0, v0
	v_rcp_f32_e32 v0, v0
	v_cvt_pk_bf16_f32 v4, v2, s0
	v_lshl_add_u64 v[2:3], v[68:69], 0, v[34:35]
	global_store_short v[2:3], v4, off
	v_cvt_pk_bf16_f32 v0, v0, s0
	v_lshl_add_u64 v[2:3], v[66:67], 0, v[34:35]
	global_store_short v[2:3], v0, off
	s_cbranch_scc1 .LBB0_118
